# four workgroup barriers per decode block (after the first 16 score rows, at the index hand-off, before and in the middle of the P.V pass)
# speedup vs baseline: 1.0117x; 1.0049x over previous
; __device__ __forceinline__ void sb_decode_stream(Frame& F, unsigned* qctr, int base, int limit) {
;     ...
;         const int bh = ((it >> 11) << 3) | (it & 7), blk = (it >> 3) & 255, h = it & 7;
;         const unsigned vn = __hip_atomic_fetch_add(qctr, 1u, __ATOMIC_RELAXED, __HIP_MEMORY_SCOPE_AGENT);
;         const float k2 = kin(12)[h] * 1.4426950408889634f;
;         int zi = 0;
;     ...
;         DEC_SCORES(A, 0);
; #pragma unroll
;         for (int i = 0; i < 16; ++i) A[i] = __builtin_nontemporal_load((const f32x4*)(CV + cb + (size_t)(2 * i) * (NH * HD)));
;         DEC_SCORES(B, 1);
;     ...
; #pragma unroll
;         for (int i = 0; i < 16; ++i) B[i] = __builtin_nontemporal_load((const f32x4*)(CV + cb + (size_t)(32 + 2 * i) * (NH * HD)));
.Ldqa_fetched:
	s_nop 0
	s_add_u32 s66, s52, s68
	s_addc_u32 s67, s53, s69
	s_lshr_b32 s18, s72, 11
	s_lshl_b32 s18, s18, 3
	s_and_b32 s19, s72, 7
	s_or_b32 s18, s18, s19
	s_lshl_b32 s18, s18, 8
	s_bfe_u32 s19, s72, 0x80003
	s_or_b32 s18, s18, s19
	s_mul_i32 s18, s18, 0x210
	s_add_u32 s70, s62, s18
	s_addc_u32 s71, s63, 0
	v_mov_b32_e32 v192, s28
	v_mul_f32_e32 v192, 0x3fb8aa3b, v192
	s_waitcnt vmcnt(34)
	v_mov_b32_e32 v152, v156
	v_mov_b32_e32 v153, v157
	v_mov_b32_e32 v154, v158
	v_mov_b32_e32 v155, v159
	v_pk_mul_f32 v[148:149], v[4:5], v[152:153]
	v_pk_fma_f32 v[148:149], v[6:7], v[154:155], v[148:149]
	global_load_dwordx4 v[4:7], v187, s[66:67] nt
	s_add_u32 s66, s66, 0x2000
	s_addc_u32 s67, s67, 0
	v_add_f32_e32 v132, v148, v149
	s_waitcnt vmcnt(34)
	v_pk_mul_f32 v[150:151], v[8:9], v[152:153]
	v_pk_fma_f32 v[150:151], v[10:11], v[154:155], v[150:151]
	global_load_dwordx4 v[8:11], v187, s[66:67] nt
	s_add_u32 s66, s66, 0x2000
	s_addc_u32 s67, s67, 0
	v_add_f32_e32 v133, v150, v151
	s_waitcnt vmcnt(34)
	v_pk_mul_f32 v[148:149], v[12:13], v[152:153]
	v_pk_fma_f32 v[148:149], v[14:15], v[154:155], v[148:149]
	global_load_dwordx4 v[12:15], v187, s[66:67] nt
	s_add_u32 s66, s66, 0x2000
	s_addc_u32 s67, s67, 0
	v_add_f32_e32 v134, v148, v149
	s_waitcnt vmcnt(34)
	v_pk_mul_f32 v[150:151], v[16:17], v[152:153]
	v_pk_fma_f32 v[150:151], v[18:19], v[154:155], v[150:151]
	global_load_dwordx4 v[16:19], v187, s[66:67] nt
	s_add_u32 s66, s66, 0x2000
	s_addc_u32 s67, s67, 0
	v_add_f32_e32 v135, v150, v151
	s_waitcnt vmcnt(34)
	v_pk_mul_f32 v[148:149], v[20:21], v[152:153]
	v_pk_fma_f32 v[148:149], v[22:23], v[154:155], v[148:149]
	global_load_dwordx4 v[20:23], v187, s[66:67] nt
	s_add_u32 s66, s66, 0x2000
	s_addc_u32 s67, s67, 0
	v_add_f32_e32 v136, v148, v149
	s_waitcnt vmcnt(34)
	v_pk_mul_f32 v[150:151], v[24:25], v[152:153]
	v_pk_fma_f32 v[150:151], v[26:27], v[154:155], v[150:151]
	global_load_dwordx4 v[24:27], v187, s[66:67] nt
	s_add_u32 s66, s66, 0x2000
	s_addc_u32 s67, s67, 0
	v_add_f32_e32 v137, v150, v151
	s_waitcnt vmcnt(34)
	v_pk_mul_f32 v[148:149], v[28:29], v[152:153]
	v_pk_fma_f32 v[148:149], v[30:31], v[154:155], v[148:149]
	global_load_dwordx4 v[28:31], v187, s[66:67] nt
	s_add_u32 s66, s66, 0x2000
	s_addc_u32 s67, s67, 0
	v_add_f32_e32 v138, v148, v149
	s_waitcnt vmcnt(34)
	v_pk_mul_f32 v[150:151], v[32:33], v[152:153]
	v_pk_fma_f32 v[150:151], v[34:35], v[154:155], v[150:151]
	global_load_dwordx4 v[32:35], v187, s[66:67] nt
	s_add_u32 s66, s66, 0x2000
	s_addc_u32 s67, s67, 0
	v_add_f32_e32 v139, v150, v151
	s_waitcnt vmcnt(34)
	v_pk_mul_f32 v[148:149], v[36:37], v[152:153]
	v_pk_fma_f32 v[148:149], v[38:39], v[154:155], v[148:149]
	global_load_dwordx4 v[36:39], v187, s[66:67] nt
	s_add_u32 s66, s66, 0x2000
	s_addc_u32 s67, s67, 0
	v_add_f32_e32 v140, v148, v149
	s_waitcnt vmcnt(34)
	v_pk_mul_f32 v[150:151], v[40:41], v[152:153]
	v_pk_fma_f32 v[150:151], v[42:43], v[154:155], v[150:151]
	global_load_dwordx4 v[40:43], v187, s[66:67] nt
	s_add_u32 s66, s66, 0x2000
	s_addc_u32 s67, s67, 0
	v_add_f32_e32 v141, v150, v151
	s_waitcnt vmcnt(34)
	v_pk_mul_f32 v[148:149], v[44:45], v[152:153]
	v_pk_fma_f32 v[148:149], v[46:47], v[154:155], v[148:149]
	global_load_dwordx4 v[44:47], v187, s[66:67] nt
	s_add_u32 s66, s66, 0x2000
	s_addc_u32 s67, s67, 0
	v_add_f32_e32 v142, v148, v149
	s_waitcnt vmcnt(34)
	v_pk_mul_f32 v[150:151], v[48:49], v[152:153]
	v_pk_fma_f32 v[150:151], v[50:51], v[154:155], v[150:151]
	global_load_dwordx4 v[48:51], v187, s[66:67] nt
	s_add_u32 s66, s66, 0x2000
	s_addc_u32 s67, s67, 0
	v_add_f32_e32 v143, v150, v151
	s_waitcnt vmcnt(34)
	v_pk_mul_f32 v[148:149], v[52:53], v[152:153]
	v_pk_fma_f32 v[148:149], v[54:55], v[154:155], v[148:149]
	global_load_dwordx4 v[52:55], v187, s[66:67] nt
	s_add_u32 s66, s66, 0x2000
	s_addc_u32 s67, s67, 0
	v_add_f32_e32 v144, v148, v149
	s_waitcnt vmcnt(34)
	v_pk_mul_f32 v[150:151], v[56:57], v[152:153]
	v_pk_fma_f32 v[150:151], v[58:59], v[154:155], v[150:151]
	global_load_dwordx4 v[56:59], v187, s[66:67] nt
	s_add_u32 s66, s66, 0x2000
	s_addc_u32 s67, s67, 0
	v_add_f32_e32 v145, v150, v151
	s_waitcnt vmcnt(34)
	v_pk_mul_f32 v[148:149], v[60:61], v[152:153]
	v_pk_fma_f32 v[148:149], v[62:63], v[154:155], v[148:149]
	global_load_dwordx4 v[60:63], v187, s[66:67] nt
	s_add_u32 s66, s66, 0x2000
	s_addc_u32 s67, s67, 0
	v_add_f32_e32 v146, v148, v149
	s_waitcnt vmcnt(34)
	v_pk_mul_f32 v[150:151], v[64:65], v[152:153]
	v_pk_fma_f32 v[150:151], v[66:67], v[154:155], v[150:151]
	global_load_dwordx4 v[64:67], v187, s[66:67] nt
	s_add_u32 s66, s66, 0x2000
	s_addc_u32 s67, s67, 0
	v_add_f32_e32 v147, v150, v151
	s_barrier
; __device__ __forceinline__ void sb_decode_stream(Frame& F, unsigned* qctr, int base, int limit) {
;     ...
;         DEC_SCORES(A, 0);
; #pragma unroll
;         for (int i = 0; i < 16; ++i) A[i] = __builtin_nontemporal_load((const f32x4*)(CV + cb + (size_t)(2 * i) * (NH * HD)));
;         DEC_SCORES(B, 1);
;     ...
; #pragma unroll
;         for (int i = 0; i < 16; ++i) B[i] = __builtin_nontemporal_load((const f32x4*)(CV + cb + (size_t)(32 + 2 * i) * (NH * HD)));
	v_add_f32_dpp v132, v132, v132 row_ror:8 row_mask:0xf bank_mask:0x3
	v_add_f32_dpp v133, v133, v133 row_ror:8 row_mask:0xf bank_mask:0x3
	v_add_f32_dpp v134, v134, v134 row_ror:8 row_mask:0xf bank_mask:0x3
	v_add_f32_dpp v135, v135, v135 row_ror:8 row_mask:0xf bank_mask:0x3
	v_add_f32_dpp v136, v136, v136 row_ror:8 row_mask:0xf bank_mask:0x3
	v_add_f32_dpp v137, v137, v137 row_ror:8 row_mask:0xf bank_mask:0x3
	v_add_f32_dpp v138, v138, v138 row_ror:8 row_mask:0xf bank_mask:0x3
	v_add_f32_dpp v139, v139, v139 row_ror:8 row_mask:0xf bank_mask:0x3
	v_add_f32_dpp v132, v140, v140 row_ror:8 row_mask:0xf bank_mask:0xc
	v_add_f32_dpp v133, v141, v141 row_ror:8 row_mask:0xf bank_mask:0xc
	v_add_f32_dpp v134, v142, v142 row_ror:8 row_mask:0xf bank_mask:0xc
	v_add_f32_dpp v135, v143, v143 row_ror:8 row_mask:0xf bank_mask:0xc
	v_add_f32_dpp v136, v144, v144 row_ror:8 row_mask:0xf bank_mask:0xc
	v_add_f32_dpp v137, v145, v145 row_ror:8 row_mask:0xf bank_mask:0xc
	v_add_f32_dpp v138, v146, v146 row_ror:8 row_mask:0xf bank_mask:0xc
	v_add_f32_dpp v139, v147, v147 row_ror:8 row_mask:0xf bank_mask:0xc
	v_add_f32_dpp v132, v132, v132 row_ror:12 row_mask:0xf bank_mask:0x5
	v_add_f32_dpp v133, v133, v133 row_ror:12 row_mask:0xf bank_mask:0x5
	v_add_f32_dpp v134, v134, v134 row_ror:12 row_mask:0xf bank_mask:0x5
	v_add_f32_dpp v135, v135, v135 row_ror:12 row_mask:0xf bank_mask:0x5
	v_add_f32_dpp v132, v136, v136 row_ror:4 row_mask:0xf bank_mask:0xa
	v_add_f32_dpp v133, v137, v137 row_ror:4 row_mask:0xf bank_mask:0xa
	v_add_f32_dpp v134, v138, v138 row_ror:4 row_mask:0xf bank_mask:0xa
	v_add_f32_dpp v135, v139, v139 row_ror:4 row_mask:0xf bank_mask:0xa
	v_add_f32_dpp v140, v132, v132 quad_perm:[2,3,0,1] row_mask:0xf bank_mask:0xf
	v_add_f32_dpp v142, v134, v134 quad_perm:[2,3,0,1] row_mask:0xf bank_mask:0xf
	v_add_f32_dpp v141, v133, v133 quad_perm:[2,3,0,1] row_mask:0xf bank_mask:0xf
	v_add_f32_dpp v143, v135, v135 quad_perm:[2,3,0,1] row_mask:0xf bank_mask:0xf
	v_cndmask_b32_e64 v132, v140, v142, s[76:77]
	v_cndmask_b32_e64 v133, v141, v143, s[76:77]
	s_nop 0
	v_add_f32_dpp v196, v132, v132 quad_perm:[1,0,3,2] row_mask:0xf bank_mask:0xf
	v_add_f32_dpp v197, v133, v133 quad_perm:[1,0,3,2] row_mask:0xf bank_mask:0xf
	v_cndmask_b32_e64 v176, v196, v197, s[78:79]
	s_waitcnt vmcnt(34)
	v_pk_mul_f32 v[148:149], v[68:69], v[152:153]
	v_pk_fma_f32 v[148:149], v[70:71], v[154:155], v[148:149]
	global_load_dwordx4 v[68:71], v187, s[66:67] nt
	s_add_u32 s66, s66, 0x2000
	s_addc_u32 s67, s67, 0
	v_add_f32_e32 v132, v148, v149
	s_waitcnt vmcnt(34)
	v_pk_mul_f32 v[150:151], v[72:73], v[152:153]
	v_pk_fma_f32 v[150:151], v[74:75], v[154:155], v[150:151]
	global_load_dwordx4 v[72:75], v187, s[66:67] nt
	s_add_u32 s66, s66, 0x2000
	s_addc_u32 s67, s67, 0
	v_add_f32_e32 v133, v150, v151
	s_waitcnt vmcnt(34)
	v_pk_mul_f32 v[148:149], v[76:77], v[152:153]
	v_pk_fma_f32 v[148:149], v[78:79], v[154:155], v[148:149]
	global_load_dwordx4 v[76:79], v187, s[66:67] nt
	s_add_u32 s66, s66, 0x2000
	s_addc_u32 s67, s67, 0
	v_add_f32_e32 v134, v148, v149
	s_waitcnt vmcnt(34)
	v_pk_mul_f32 v[150:151], v[80:81], v[152:153]
	v_pk_fma_f32 v[150:151], v[82:83], v[154:155], v[150:151]
	global_load_dwordx4 v[80:83], v187, s[66:67] nt
	s_add_u32 s66, s66, 0x2000
	s_addc_u32 s67, s67, 0
	v_add_f32_e32 v135, v150, v151
	s_waitcnt vmcnt(34)
	v_pk_mul_f32 v[148:149], v[84:85], v[152:153]
	v_pk_fma_f32 v[148:149], v[86:87], v[154:155], v[148:149]
	global_load_dwordx4 v[84:87], v187, s[66:67] nt
	s_add_u32 s66, s66, 0x2000
	s_addc_u32 s67, s67, 0
	v_add_f32_e32 v136, v148, v149
	s_waitcnt vmcnt(34)
	v_pk_mul_f32 v[150:151], v[88:89], v[152:153]
	v_pk_fma_f32 v[150:151], v[90:91], v[154:155], v[150:151]
	global_load_dwordx4 v[88:91], v187, s[66:67] nt
	s_add_u32 s66, s66, 0x2000
	s_addc_u32 s67, s67, 0
	v_add_f32_e32 v137, v150, v151
	s_waitcnt vmcnt(34)
	v_pk_mul_f32 v[148:149], v[92:93], v[152:153]
	v_pk_fma_f32 v[148:149], v[94:95], v[154:155], v[148:149]
	global_load_dwordx4 v[92:95], v187, s[66:67] nt
	s_add_u32 s66, s66, 0x2000
	s_addc_u32 s67, s67, 0
	v_add_f32_e32 v138, v148, v149
	s_waitcnt vmcnt(34)
	v_pk_mul_f32 v[150:151], v[96:97], v[152:153]
	v_pk_fma_f32 v[150:151], v[98:99], v[154:155], v[150:151]
	global_load_dwordx4 v[96:99], v187, s[66:67] nt
	s_add_u32 s66, s66, 0x2000
	s_addc_u32 s67, s67, 0
	v_add_f32_e32 v139, v150, v151
	s_waitcnt vmcnt(34)
	v_pk_mul_f32 v[148:149], v[100:101], v[152:153]
	v_pk_fma_f32 v[148:149], v[102:103], v[154:155], v[148:149]
	global_load_dwordx4 v[100:103], v187, s[66:67] nt
	s_add_u32 s66, s66, 0x2000
	s_addc_u32 s67, s67, 0
	v_add_f32_e32 v140, v148, v149
	s_waitcnt vmcnt(34)
	v_pk_mul_f32 v[150:151], v[104:105], v[152:153]
	v_pk_fma_f32 v[150:151], v[106:107], v[154:155], v[150:151]
	global_load_dwordx4 v[104:107], v187, s[66:67] nt
	s_add_u32 s66, s66, 0x2000
	s_addc_u32 s67, s67, 0
	v_add_f32_e32 v141, v150, v151
	s_waitcnt vmcnt(34)
	v_pk_mul_f32 v[148:149], v[108:109], v[152:153]
	v_pk_fma_f32 v[148:149], v[110:111], v[154:155], v[148:149]
	global_load_dwordx4 v[108:111], v187, s[66:67] nt
	s_add_u32 s66, s66, 0x2000
	s_addc_u32 s67, s67, 0
	v_add_f32_e32 v142, v148, v149
	s_waitcnt vmcnt(34)
	v_pk_mul_f32 v[150:151], v[112:113], v[152:153]
	v_pk_fma_f32 v[150:151], v[114:115], v[154:155], v[150:151]
	global_load_dwordx4 v[112:115], v187, s[66:67] nt
	s_add_u32 s66, s66, 0x2000
	s_addc_u32 s67, s67, 0
	v_add_f32_e32 v143, v150, v151
	s_waitcnt vmcnt(34)
	v_pk_mul_f32 v[148:149], v[116:117], v[152:153]
	v_pk_fma_f32 v[148:149], v[118:119], v[154:155], v[148:149]
	global_load_dwordx4 v[116:119], v187, s[66:67] nt
	s_add_u32 s66, s66, 0x2000
	s_addc_u32 s67, s67, 0
	v_add_f32_e32 v144, v148, v149
	s_waitcnt vmcnt(34)
	v_pk_mul_f32 v[150:151], v[120:121], v[152:153]
	v_pk_fma_f32 v[150:151], v[122:123], v[154:155], v[150:151]
	global_load_dwordx4 v[120:123], v187, s[66:67] nt
	s_add_u32 s66, s66, 0x2000
	s_addc_u32 s67, s67, 0
	v_add_f32_e32 v145, v150, v151
	s_waitcnt vmcnt(34)
	v_pk_mul_f32 v[148:149], v[124:125], v[152:153]
	v_pk_fma_f32 v[148:149], v[126:127], v[154:155], v[148:149]
	global_load_dwordx4 v[124:127], v187, s[66:67] nt
	s_add_u32 s66, s66, 0x2000
	s_addc_u32 s67, s67, 0
	v_add_f32_e32 v146, v148, v149
	s_waitcnt vmcnt(34)
	v_pk_mul_f32 v[150:151], v[128:129], v[152:153]
	v_pk_fma_f32 v[150:151], v[130:131], v[154:155], v[150:151]
	global_load_dwordx4 v[128:131], v187, s[66:67] nt
	s_add_u32 s66, s66, 0x2000
	s_addc_u32 s67, s67, 0
	v_add_f32_e32 v147, v150, v151
	s_waitcnt vmcnt(32)
	v_readfirstlane_b32 s2, v191
	v_mov_b32_e32 v200, s37
	s_cmp_eq_u32 s94, 0
	s_cbranch_scc0 .Ldqa_sh2
	v_mov_b32_e32 v201, s2
	ds_write_b32 v200, v201
	s_waitcnt lgkmcnt(0)
; __device__ __forceinline__ void sb_decode_stream(Frame& F, unsigned* qctr, int base, int limit) {
;     ...
;         const float z = __builtin_bit_cast(float, zi);
;         const float e = __builtin_amdgcn_exp2f(-(z * k1 + k2));
;         const float be = __builtin_amdgcn_rcpf(1.0f + e), m = 1.0f - be;
;         float s = m;
; #pragma unroll
;         for (int o = 1; o < 64; o <<= 1) { const float t = __shfl_down(s, o); if (lane + o < 64) s *= t; }
;         const float tot = __shfl(s, 0);
;         const float sx = __shfl_down(s, 1);
;         const float a = be * (lane < 63 ? sx : 1.0f);
;         int itn = (int)(__builtin_amdgcn_readfirstlane(vn) >> 6); const bool more = itn < limit; itn = more ? itn + base : it;
;         const int bn = itn >> 11, hn = itn & 7, p0n = ((itn >> 3) & 255) * 64;
;         const int pagen = PT[bn * NPAGES + (p0n >> 7)];
;         const size_t cbn = (((size_t)pagen * PAGE + (p0n & 127)) * NH + hn) * HD + lo;
;         const size_t stepn = more ? (size_t)(NH * HD) : 0;
.Ldqa_sh2:
	s_barrier
	ds_read_b32 v201, v200
	s_xor_b32 s37, s37, 4
	s_waitcnt lgkmcnt(0)
	v_readfirstlane_b32 s2, v201
	s_nop 0
	s_lshr_b32 s73, s2, 6
	s_cmp_lt_u32 s73, 0x1800
	s_cselect_b32 s31, 1, 0
	s_add_u32 s73, s73, s94
	s_min_u32 s73, s73, 0x17ff
	s_cmp_eq_u32 s31, 1
	s_cselect_b32 s73, s73, s72
	s_lshr_b32 s6, s73, 11
	s_and_b32 s7, s73, 7
	s_bfe_u32 s8, s73, 0x80003
	s_lshl_b32 s9, s6, 7
	s_lshr_b32 s10, s8, 1
	s_or_b32 s9, s9, s10
	s_lshl_b32 s9, s9, 2
	s_lshl_b32 s10, s7, 2
	s_load_dword s29, s[54:55], s9
	s_load_dword s30, s[56:57], s10
	v_add_f32_dpp v132, v132, v132 row_ror:8 row_mask:0xf bank_mask:0x3
	v_add_f32_dpp v133, v133, v133 row_ror:8 row_mask:0xf bank_mask:0x3
	v_add_f32_dpp v134, v134, v134 row_ror:8 row_mask:0xf bank_mask:0x3
	v_add_f32_dpp v135, v135, v135 row_ror:8 row_mask:0xf bank_mask:0x3
	v_add_f32_dpp v136, v136, v136 row_ror:8 row_mask:0xf bank_mask:0x3
	v_add_f32_dpp v137, v137, v137 row_ror:8 row_mask:0xf bank_mask:0x3
	v_add_f32_dpp v138, v138, v138 row_ror:8 row_mask:0xf bank_mask:0x3
	v_add_f32_dpp v139, v139, v139 row_ror:8 row_mask:0xf bank_mask:0x3
	v_add_f32_dpp v132, v140, v140 row_ror:8 row_mask:0xf bank_mask:0xc
	v_add_f32_dpp v133, v141, v141 row_ror:8 row_mask:0xf bank_mask:0xc
	v_add_f32_dpp v134, v142, v142 row_ror:8 row_mask:0xf bank_mask:0xc
	v_add_f32_dpp v135, v143, v143 row_ror:8 row_mask:0xf bank_mask:0xc
	v_add_f32_dpp v136, v144, v144 row_ror:8 row_mask:0xf bank_mask:0xc
	v_add_f32_dpp v137, v145, v145 row_ror:8 row_mask:0xf bank_mask:0xc
	v_add_f32_dpp v138, v146, v146 row_ror:8 row_mask:0xf bank_mask:0xc
	v_add_f32_dpp v139, v147, v147 row_ror:8 row_mask:0xf bank_mask:0xc
	v_add_f32_dpp v132, v132, v132 row_ror:12 row_mask:0xf bank_mask:0x5
	v_add_f32_dpp v133, v133, v133 row_ror:12 row_mask:0xf bank_mask:0x5
	v_add_f32_dpp v134, v134, v134 row_ror:12 row_mask:0xf bank_mask:0x5
	v_add_f32_dpp v135, v135, v135 row_ror:12 row_mask:0xf bank_mask:0x5
	v_add_f32_dpp v132, v136, v136 row_ror:4 row_mask:0xf bank_mask:0xa
	v_add_f32_dpp v133, v137, v137 row_ror:4 row_mask:0xf bank_mask:0xa
	v_add_f32_dpp v134, v138, v138 row_ror:4 row_mask:0xf bank_mask:0xa
	v_add_f32_dpp v135, v139, v139 row_ror:4 row_mask:0xf bank_mask:0xa
	v_add_f32_dpp v140, v132, v132 quad_perm:[2,3,0,1] row_mask:0xf bank_mask:0xf
	v_add_f32_dpp v142, v134, v134 quad_perm:[2,3,0,1] row_mask:0xf bank_mask:0xf
	v_add_f32_dpp v141, v133, v133 quad_perm:[2,3,0,1] row_mask:0xf bank_mask:0xf
	v_add_f32_dpp v143, v135, v135 quad_perm:[2,3,0,1] row_mask:0xf bank_mask:0xf
	v_cndmask_b32_e64 v132, v140, v142, s[76:77]
	v_cndmask_b32_e64 v133, v141, v143, s[76:77]
	s_nop 0
	v_add_f32_dpp v196, v132, v132 quad_perm:[1,0,3,2] row_mask:0xf bank_mask:0xf
	v_add_f32_dpp v197, v133, v133 quad_perm:[1,0,3,2] row_mask:0xf bank_mask:0xf
	v_cndmask_b32_e64 v177, v196, v197, s[78:79]
	s_nop 1
	v_permlane16_swap_b32_e32 v176, v177
	v_add_f32_e32 v178, v176, v177
	v_mul_f32_e32 v178, 0x3e0293ee, v178
	v_add_f32_e32 v178, v178, v192
	v_exp_f32_e64 v198, -v178
	s_nop 0
	v_add_f32_e32 v198, 1.0, v198
	v_rcp_f32_e32 v179, v198
	s_nop 0
	v_sub_f32_e32 v180, 1.0, v179
	v_mov_b32_e32 v181, v180
	s_nop 1
	v_permlane32_swap_b32_e32 v180, v181
	v_mul_f32_e32 v183, v180, v181
	s_nop 1
	v_mul_f32_dpp v183, v183, v183 row_shl:1 row_mask:0xf bank_mask:0xf
	s_nop 1
	v_mul_f32_dpp v183, v183, v183 row_shl:2 row_mask:0xf bank_mask:0xf
	s_nop 1
	v_mul_f32_dpp v183, v183, v183 row_shl:4 row_mask:0xf bank_mask:0xf
	s_nop 1
	v_mul_f32_dpp v183, v183, v183 row_shl:8 row_mask:0xf bank_mask:0xf
	s_nop 0
	v_readlane_b32 s33, v183, 16
	v_mov_b32_e32 v184, 1.0
	s_nop 0
	v_mov_b32_e32 v185, s33
	s_nop 1
	v_mul_f32_dpp v183, v183, v185 quad_perm:[0,1,2,3] row_mask:0x5 bank_mask:0xf
	v_mov_b32_dpp v184, v185 quad_perm:[0,1,2,3] row_mask:0x5 bank_mask:0xf
	s_nop 1
	v_mov_b32_dpp v184, v183 row_shl:1 row_mask:0xf bank_mask:0xf
	v_mul_f32_e32 v186, v179, v184
	s_nop 1
	v_mul_f32_dpp v186, v186, v181 quad_perm:[0,1,2,3] row_mask:0x3 bank_mask:0xf
	s_cmp_eq_u32 s31, 0
	s_cbranch_scc1 .Ldqa_tail
	s_waitcnt lgkmcnt(0)
	s_mov_b32 s12, s29
	s_mov_b32 s13, 0
	s_lshl_b64 s[12:13], s[12:13], 19
	s_and_b32 s14, s8, 1
	s_lshl_b32 s14, s14, 18
	s_lshl_b32 s15, s7, 9
	s_or_b32 s14, s14, s15
	s_or_b32 s80, s12, s14
	s_mov_b32 s81, s13
	s_add_u32 s64, s50, s80
	s_addc_u32 s65, s51, s81
	s_mul_i32 s16, s6, 0x7040
	s_add_u32 s16, s16, s15
	s_add_u32 s16, s60, s16
	s_addc_u32 s17, s61, 0
	global_load_dwordx4 v[156:159], v193, s[16:17]
	s_barrier
; __device__ __forceinline__ void sb_decode_stream(Frame& F, unsigned* qctr, int base, int limit) {
;     ...
;         f32x4 o4 = {0.f, 0.f, 0.f, 0.f};
; #pragma unroll
;         for (int i = 0; i < 16; ++i) { const float aj = __shfl(a, 2 * i + half); o4 += aj * A[i]; }
;         const f32x4 q4n = *(const f32x4*)(SSP(S_PROJ) + (size_t)bn * IN_COLS + hn * HD + 4 * l32);
; #pragma unroll
;         for (int i = 0; i < 16; ++i) A[i] = __builtin_nontemporal_load((const f32x4*)(CK + cbn + (size_t)(2 * i) * stepn));
; #pragma unroll
;         for (int i = 0; i < 16; ++i) { const float aj = __shfl(a, 32 + 2 * i + half); o4 += aj * B[i]; }
; #pragma unroll
;         for (int i = 0; i < 16; ++i) B[i] = __builtin_nontemporal_load((const f32x4*)(CK + cbn + (size_t)(32 + 2 * i) * stepn));
	v_mov_b32_e32 v160, 0
	v_mov_b32_e32 v161, 0
	v_mov_b32_e32 v162, 0
	v_mov_b32_e32 v163, 0
	v_mov_b32_e32 v164, 0
	v_mov_b32_e32 v165, 0
	v_mov_b32_e32 v166, 0
	v_mov_b32_e32 v167, 0
	ds_bpermute_b32 v168, v188, v186 offset:0
	ds_bpermute_b32 v170, v188, v186 offset:4
	ds_bpermute_b32 v172, v188, v186 offset:8
	ds_bpermute_b32 v174, v188, v186 offset:12
	s_waitcnt vmcnt(32) lgkmcnt(3)
	v_pk_fma_f32 v[160:161], v[4:5], v[168:169], v[160:161] op_sel_hi:[1,0,1]
	v_pk_fma_f32 v[162:163], v[6:7], v[168:169], v[162:163] op_sel_hi:[1,0,1]
	global_load_dwordx4 v[4:7], v187, s[64:65] nt
	s_add_u32 s64, s64, 0x2000
	s_addc_u32 s65, s65, 0
	ds_bpermute_b32 v168, v188, v186 offset:16
	s_waitcnt vmcnt(32) lgkmcnt(3)
	v_pk_fma_f32 v[164:165], v[8:9], v[170:171], v[164:165] op_sel_hi:[1,0,1]
	v_pk_fma_f32 v[166:167], v[10:11], v[170:171], v[166:167] op_sel_hi:[1,0,1]
	global_load_dwordx4 v[8:11], v187, s[64:65] nt
	s_add_u32 s64, s64, 0x2000
	s_addc_u32 s65, s65, 0
	ds_bpermute_b32 v170, v188, v186 offset:20
	s_waitcnt vmcnt(32) lgkmcnt(3)
	v_pk_fma_f32 v[160:161], v[12:13], v[172:173], v[160:161] op_sel_hi:[1,0,1]
	v_pk_fma_f32 v[162:163], v[14:15], v[172:173], v[162:163] op_sel_hi:[1,0,1]
	global_load_dwordx4 v[12:15], v187, s[64:65] nt
	s_add_u32 s64, s64, 0x2000
	s_addc_u32 s65, s65, 0
	ds_bpermute_b32 v172, v188, v186 offset:24
	s_waitcnt vmcnt(32) lgkmcnt(3)
	v_pk_fma_f32 v[164:165], v[16:17], v[174:175], v[164:165] op_sel_hi:[1,0,1]
	v_pk_fma_f32 v[166:167], v[18:19], v[174:175], v[166:167] op_sel_hi:[1,0,1]
	global_load_dwordx4 v[16:19], v187, s[64:65] nt
	s_add_u32 s64, s64, 0x2000
	s_addc_u32 s65, s65, 0
	ds_bpermute_b32 v174, v188, v186 offset:28
	s_waitcnt vmcnt(32) lgkmcnt(3)
	v_pk_fma_f32 v[160:161], v[20:21], v[168:169], v[160:161] op_sel_hi:[1,0,1]
	v_pk_fma_f32 v[162:163], v[22:23], v[168:169], v[162:163] op_sel_hi:[1,0,1]
	global_load_dwordx4 v[20:23], v187, s[64:65] nt
	s_add_u32 s64, s64, 0x2000
	s_addc_u32 s65, s65, 0
	ds_bpermute_b32 v168, v188, v186 offset:32
	s_waitcnt vmcnt(32) lgkmcnt(3)
	v_pk_fma_f32 v[164:165], v[24:25], v[170:171], v[164:165] op_sel_hi:[1,0,1]
	v_pk_fma_f32 v[166:167], v[26:27], v[170:171], v[166:167] op_sel_hi:[1,0,1]
	global_load_dwordx4 v[24:27], v187, s[64:65] nt
	s_add_u32 s64, s64, 0x2000
	s_addc_u32 s65, s65, 0
	ds_bpermute_b32 v170, v188, v186 offset:36
	s_waitcnt vmcnt(32) lgkmcnt(3)
	v_pk_fma_f32 v[160:161], v[28:29], v[172:173], v[160:161] op_sel_hi:[1,0,1]
	v_pk_fma_f32 v[162:163], v[30:31], v[172:173], v[162:163] op_sel_hi:[1,0,1]
	global_load_dwordx4 v[28:31], v187, s[64:65] nt
	s_add_u32 s64, s64, 0x2000
	s_addc_u32 s65, s65, 0
	ds_bpermute_b32 v172, v188, v186 offset:40
	s_waitcnt vmcnt(32) lgkmcnt(3)
	v_pk_fma_f32 v[164:165], v[32:33], v[174:175], v[164:165] op_sel_hi:[1,0,1]
	v_pk_fma_f32 v[166:167], v[34:35], v[174:175], v[166:167] op_sel_hi:[1,0,1]
	global_load_dwordx4 v[32:35], v187, s[64:65] nt
	s_add_u32 s64, s64, 0x2000
	s_addc_u32 s65, s65, 0
	ds_bpermute_b32 v174, v188, v186 offset:44
	s_waitcnt vmcnt(32) lgkmcnt(3)
	v_pk_fma_f32 v[160:161], v[36:37], v[168:169], v[160:161] op_sel_hi:[1,0,1]
	v_pk_fma_f32 v[162:163], v[38:39], v[168:169], v[162:163] op_sel_hi:[1,0,1]
	global_load_dwordx4 v[36:39], v187, s[64:65] nt
	s_add_u32 s64, s64, 0x2000
	s_addc_u32 s65, s65, 0
	ds_bpermute_b32 v168, v188, v186 offset:48
	s_waitcnt vmcnt(32) lgkmcnt(3)
	v_pk_fma_f32 v[164:165], v[40:41], v[170:171], v[164:165] op_sel_hi:[1,0,1]
	v_pk_fma_f32 v[166:167], v[42:43], v[170:171], v[166:167] op_sel_hi:[1,0,1]
	global_load_dwordx4 v[40:43], v187, s[64:65] nt
	s_add_u32 s64, s64, 0x2000
	s_addc_u32 s65, s65, 0
	ds_bpermute_b32 v170, v188, v186 offset:52
	s_waitcnt vmcnt(32) lgkmcnt(3)
	v_pk_fma_f32 v[160:161], v[44:45], v[172:173], v[160:161] op_sel_hi:[1,0,1]
	v_pk_fma_f32 v[162:163], v[46:47], v[172:173], v[162:163] op_sel_hi:[1,0,1]
	global_load_dwordx4 v[44:47], v187, s[64:65] nt
	s_add_u32 s64, s64, 0x2000
	s_addc_u32 s65, s65, 0
	ds_bpermute_b32 v172, v188, v186 offset:56
	s_waitcnt vmcnt(32) lgkmcnt(3)
	v_pk_fma_f32 v[164:165], v[48:49], v[174:175], v[164:165] op_sel_hi:[1,0,1]
	v_pk_fma_f32 v[166:167], v[50:51], v[174:175], v[166:167] op_sel_hi:[1,0,1]
	global_load_dwordx4 v[48:51], v187, s[64:65] nt
	s_add_u32 s64, s64, 0x2000
	s_addc_u32 s65, s65, 0
	ds_bpermute_b32 v174, v188, v186 offset:60
	s_waitcnt vmcnt(32) lgkmcnt(3)
	v_pk_fma_f32 v[160:161], v[52:53], v[168:169], v[160:161] op_sel_hi:[1,0,1]
	v_pk_fma_f32 v[162:163], v[54:55], v[168:169], v[162:163] op_sel_hi:[1,0,1]
	global_load_dwordx4 v[52:55], v187, s[64:65] nt
	s_add_u32 s64, s64, 0x2000
	s_addc_u32 s65, s65, 0
	ds_bpermute_b32 v168, v188, v186 offset:64
	s_waitcnt vmcnt(32) lgkmcnt(3)
	v_pk_fma_f32 v[164:165], v[56:57], v[170:171], v[164:165] op_sel_hi:[1,0,1]
	v_pk_fma_f32 v[166:167], v[58:59], v[170:171], v[166:167] op_sel_hi:[1,0,1]
	global_load_dwordx4 v[56:59], v187, s[64:65] nt
	s_add_u32 s64, s64, 0x2000
	s_addc_u32 s65, s65, 0
	ds_bpermute_b32 v170, v188, v186 offset:68
	s_waitcnt vmcnt(32) lgkmcnt(3)
	v_pk_fma_f32 v[160:161], v[60:61], v[172:173], v[160:161] op_sel_hi:[1,0,1]
	v_pk_fma_f32 v[162:163], v[62:63], v[172:173], v[162:163] op_sel_hi:[1,0,1]
	global_load_dwordx4 v[60:63], v187, s[64:65] nt
	s_add_u32 s64, s64, 0x2000
	s_addc_u32 s65, s65, 0
	ds_bpermute_b32 v172, v188, v186 offset:72
	s_waitcnt vmcnt(32) lgkmcnt(3)
	v_pk_fma_f32 v[164:165], v[64:65], v[174:175], v[164:165] op_sel_hi:[1,0,1]
	v_pk_fma_f32 v[166:167], v[66:67], v[174:175], v[166:167] op_sel_hi:[1,0,1]
	global_load_dwordx4 v[64:67], v187, s[64:65] nt
	s_add_u32 s64, s64, 0x2000
	s_addc_u32 s65, s65, 0
	s_barrier
; __device__ __forceinline__ void sb_decode_stream(Frame& F, unsigned* qctr, int base, int limit) {
;     ...
;         f32x4 o4 = {0.f, 0.f, 0.f, 0.f};
; #pragma unroll
;         for (int i = 0; i < 16; ++i) { const float aj = __shfl(a, 2 * i + half); o4 += aj * A[i]; }
;         const f32x4 q4n = *(const f32x4*)(SSP(S_PROJ) + (size_t)bn * IN_COLS + hn * HD + 4 * l32);
; #pragma unroll
;         for (int i = 0; i < 16; ++i) A[i] = __builtin_nontemporal_load((const f32x4*)(CK + cbn + (size_t)(2 * i) * stepn));
; #pragma unroll
;         for (int i = 0; i < 16; ++i) { const float aj = __shfl(a, 32 + 2 * i + half); o4 += aj * B[i]; }
; #pragma unroll
;         for (int i = 0; i < 16; ++i) B[i] = __builtin_nontemporal_load((const f32x4*)(CK + cbn + (size_t)(32 + 2 * i) * stepn));
;         o4.x += __shfl_xor(o4.x, 32); o4.y += __shfl_xor(o4.y, 32); o4.z += __shfl_xor(o4.z, 32); o4.w += __shfl_xor(o4.w, 32);
;         float* P = SSP(S_PART) + ((size_t)bh * DSEG + blk) * DPART;
;         if (half == 0) *(f32x4*)(P + 4 * l32) = o4; if (lane == 0) P[128] = tot;
;         if (!more) break;
;         it = itn; cb = cbn; q4 = q4n;
	ds_bpermute_b32 v174, v188, v186 offset:76
	s_waitcnt vmcnt(32) lgkmcnt(3)
	v_pk_fma_f32 v[160:161], v[68:69], v[168:169], v[160:161] op_sel_hi:[1,0,1]
	v_pk_fma_f32 v[162:163], v[70:71], v[168:169], v[162:163] op_sel_hi:[1,0,1]
	global_load_dwordx4 v[68:71], v187, s[64:65] nt
	s_add_u32 s64, s64, 0x2000
	s_addc_u32 s65, s65, 0
	ds_bpermute_b32 v168, v188, v186 offset:80
	s_waitcnt vmcnt(32) lgkmcnt(3)
	v_pk_fma_f32 v[164:165], v[72:73], v[170:171], v[164:165] op_sel_hi:[1,0,1]
	v_pk_fma_f32 v[166:167], v[74:75], v[170:171], v[166:167] op_sel_hi:[1,0,1]
	global_load_dwordx4 v[72:75], v187, s[64:65] nt
	s_add_u32 s64, s64, 0x2000
	s_addc_u32 s65, s65, 0
	ds_bpermute_b32 v170, v188, v186 offset:84
	s_waitcnt vmcnt(32) lgkmcnt(3)
	v_pk_fma_f32 v[160:161], v[76:77], v[172:173], v[160:161] op_sel_hi:[1,0,1]
	v_pk_fma_f32 v[162:163], v[78:79], v[172:173], v[162:163] op_sel_hi:[1,0,1]
	global_load_dwordx4 v[76:79], v187, s[64:65] nt
	s_add_u32 s64, s64, 0x2000
	s_addc_u32 s65, s65, 0
	ds_bpermute_b32 v172, v188, v186 offset:88
	s_waitcnt vmcnt(32) lgkmcnt(3)
	v_pk_fma_f32 v[164:165], v[80:81], v[174:175], v[164:165] op_sel_hi:[1,0,1]
	v_pk_fma_f32 v[166:167], v[82:83], v[174:175], v[166:167] op_sel_hi:[1,0,1]
	global_load_dwordx4 v[80:83], v187, s[64:65] nt
	s_add_u32 s64, s64, 0x2000
	s_addc_u32 s65, s65, 0
	ds_bpermute_b32 v174, v188, v186 offset:92
	s_waitcnt vmcnt(32) lgkmcnt(3)
	v_pk_fma_f32 v[160:161], v[84:85], v[168:169], v[160:161] op_sel_hi:[1,0,1]
	v_pk_fma_f32 v[162:163], v[86:87], v[168:169], v[162:163] op_sel_hi:[1,0,1]
	global_load_dwordx4 v[84:87], v187, s[64:65] nt
	s_add_u32 s64, s64, 0x2000
	s_addc_u32 s65, s65, 0
	ds_bpermute_b32 v168, v188, v186 offset:96
	s_waitcnt vmcnt(32) lgkmcnt(3)
	v_pk_fma_f32 v[164:165], v[88:89], v[170:171], v[164:165] op_sel_hi:[1,0,1]
	v_pk_fma_f32 v[166:167], v[90:91], v[170:171], v[166:167] op_sel_hi:[1,0,1]
	global_load_dwordx4 v[88:91], v187, s[64:65] nt
	s_add_u32 s64, s64, 0x2000
	s_addc_u32 s65, s65, 0
	ds_bpermute_b32 v170, v188, v186 offset:100
	s_waitcnt vmcnt(32) lgkmcnt(3)
	v_pk_fma_f32 v[160:161], v[92:93], v[172:173], v[160:161] op_sel_hi:[1,0,1]
	v_pk_fma_f32 v[162:163], v[94:95], v[172:173], v[162:163] op_sel_hi:[1,0,1]
	global_load_dwordx4 v[92:95], v187, s[64:65] nt
	s_add_u32 s64, s64, 0x2000
	s_addc_u32 s65, s65, 0
	ds_bpermute_b32 v172, v188, v186 offset:104
	s_waitcnt vmcnt(32) lgkmcnt(3)
	v_pk_fma_f32 v[164:165], v[96:97], v[174:175], v[164:165] op_sel_hi:[1,0,1]
	v_pk_fma_f32 v[166:167], v[98:99], v[174:175], v[166:167] op_sel_hi:[1,0,1]
	global_load_dwordx4 v[96:99], v187, s[64:65] nt
	s_add_u32 s64, s64, 0x2000
	s_addc_u32 s65, s65, 0
	ds_bpermute_b32 v174, v188, v186 offset:108
	s_waitcnt vmcnt(32) lgkmcnt(3)
	v_pk_fma_f32 v[160:161], v[100:101], v[168:169], v[160:161] op_sel_hi:[1,0,1]
	v_pk_fma_f32 v[162:163], v[102:103], v[168:169], v[162:163] op_sel_hi:[1,0,1]
	global_load_dwordx4 v[100:103], v187, s[64:65] nt
	s_add_u32 s64, s64, 0x2000
	s_addc_u32 s65, s65, 0
	ds_bpermute_b32 v168, v188, v186 offset:112
	s_waitcnt vmcnt(32) lgkmcnt(3)
	v_pk_fma_f32 v[164:165], v[104:105], v[170:171], v[164:165] op_sel_hi:[1,0,1]
	v_pk_fma_f32 v[166:167], v[106:107], v[170:171], v[166:167] op_sel_hi:[1,0,1]
	global_load_dwordx4 v[104:107], v187, s[64:65] nt
	s_add_u32 s64, s64, 0x2000
	s_addc_u32 s65, s65, 0
	ds_bpermute_b32 v170, v188, v186 offset:116
	s_waitcnt vmcnt(32) lgkmcnt(3)
	v_pk_fma_f32 v[160:161], v[108:109], v[172:173], v[160:161] op_sel_hi:[1,0,1]
	v_pk_fma_f32 v[162:163], v[110:111], v[172:173], v[162:163] op_sel_hi:[1,0,1]
	global_load_dwordx4 v[108:111], v187, s[64:65] nt
	s_add_u32 s64, s64, 0x2000
	s_addc_u32 s65, s65, 0
	ds_bpermute_b32 v172, v188, v186 offset:120
	s_waitcnt vmcnt(32) lgkmcnt(3)
	v_pk_fma_f32 v[164:165], v[112:113], v[174:175], v[164:165] op_sel_hi:[1,0,1]
	v_pk_fma_f32 v[166:167], v[114:115], v[174:175], v[166:167] op_sel_hi:[1,0,1]
	global_load_dwordx4 v[112:115], v187, s[64:65] nt
	s_add_u32 s64, s64, 0x2000
	s_addc_u32 s65, s65, 0
	ds_bpermute_b32 v174, v188, v186 offset:124
	s_waitcnt vmcnt(32) lgkmcnt(3)
	v_pk_fma_f32 v[160:161], v[116:117], v[168:169], v[160:161] op_sel_hi:[1,0,1]
	v_pk_fma_f32 v[162:163], v[118:119], v[168:169], v[162:163] op_sel_hi:[1,0,1]
	global_load_dwordx4 v[116:119], v187, s[64:65] nt
	s_add_u32 s64, s64, 0x2000
	s_addc_u32 s65, s65, 0
	s_waitcnt vmcnt(32) lgkmcnt(2)
	v_pk_fma_f32 v[164:165], v[120:121], v[170:171], v[164:165] op_sel_hi:[1,0,1]
	v_pk_fma_f32 v[166:167], v[122:123], v[170:171], v[166:167] op_sel_hi:[1,0,1]
	global_load_dwordx4 v[120:123], v187, s[64:65] nt
	s_add_u32 s64, s64, 0x2000
	s_addc_u32 s65, s65, 0
	s_waitcnt vmcnt(32) lgkmcnt(1)
	v_pk_fma_f32 v[160:161], v[124:125], v[172:173], v[160:161] op_sel_hi:[1,0,1]
	v_pk_fma_f32 v[162:163], v[126:127], v[172:173], v[162:163] op_sel_hi:[1,0,1]
	global_load_dwordx4 v[124:127], v187, s[64:65] nt
	s_add_u32 s64, s64, 0x2000
	s_addc_u32 s65, s65, 0
	s_waitcnt vmcnt(32) lgkmcnt(0)
	v_pk_fma_f32 v[164:165], v[128:129], v[174:175], v[164:165] op_sel_hi:[1,0,1]
	v_pk_fma_f32 v[166:167], v[130:131], v[174:175], v[166:167] op_sel_hi:[1,0,1]
	global_load_dwordx4 v[128:131], v187, s[64:65] nt
	s_add_u32 s64, s64, 0x2000
	s_addc_u32 s65, s65, 0
	s_nop 1
	v_pk_add_f32 v[160:161], v[160:161], v[164:165]
	v_pk_add_f32 v[162:163], v[162:163], v[166:167]
	s_nop 1
	v_mov_b32_e32 v164, v160
	v_mov_b32_e32 v165, v161
	v_mov_b32_e32 v166, v162
	v_mov_b32_e32 v167, v163
	v_permlane32_swap_b32_e32 v160, v164
	v_permlane32_swap_b32_e32 v161, v165
	v_permlane32_swap_b32_e32 v162, v166
	v_permlane32_swap_b32_e32 v163, v167
	v_pk_add_f32 v[160:161], v[160:161], v[164:165]
	v_pk_add_f32 v[162:163], v[162:163], v[166:167]
	s_nop 1
	s_mov_b32 exec_hi, 0
	global_store_dwordx4 v193, v[160:163], s[70:71]
	s_mov_b32 exec_lo, 1
	global_store_dword v189, v183, s[70:71] offset:512
	s_mov_b64 exec, -1
	s_mov_b32 s72, s73
	s_branch .Ldqa_loop

; __device__ __forceinline__ void sb_decode_stream(Frame& F, unsigned* qctr, int base, int limit) {
;     ...
;         const float z = __builtin_bit_cast(float, zi);
;         const float e = __builtin_amdgcn_exp2f(-(z * k1 + k2));
;         const float be = __builtin_amdgcn_rcpf(1.0f + e), m = 1.0f - be;
;         float s = m;
; #pragma unroll
;         for (int o = 1; o < 64; o <<= 1) { const float t = __shfl_down(s, o); if (lane + o < 64) s *= t; }
;         const float tot = __shfl(s, 0);
;         const float sx = __shfl_down(s, 1);
;         const float a = be * (lane < 63 ? sx : 1.0f);
;         int itn = (int)(__builtin_amdgcn_readfirstlane(vn) >> 6); const bool more = itn < limit; itn = more ? itn + base : it;
;         const int bn = itn >> 11, hn = itn & 7, p0n = ((itn >> 3) & 255) * 64;
;         const int pagen = PT[bn * NPAGES + (p0n >> 7)];
;         const size_t cbn = (((size_t)pagen * PAGE + (p0n & 127)) * NH + hn) * HD + lo;
;         const size_t stepn = more ? (size_t)(NH * HD) : 0;
.Ldqc_sh2:
	s_barrier
	ds_read_b32 v201, v200
	s_xor_b32 s37, s37, 4
	s_waitcnt lgkmcnt(0)
	v_readfirstlane_b32 s2, v201
	s_nop 0
	s_lshr_b32 s73, s2, 6
	s_cmp_lt_u32 s73, 0x2800
	s_cselect_b32 s31, 1, 0
	s_add_u32 s73, s73, s94
	s_min_u32 s73, s73, 0x27ff
	s_add_u32 s73, s73, 0x1800
	s_cmp_eq_u32 s31, 1
	s_cselect_b32 s73, s73, s72
	s_lshr_b32 s6, s73, 11
	s_and_b32 s7, s73, 7
	s_bfe_u32 s8, s73, 0x80003
	s_lshl_b32 s9, s6, 7
	s_lshr_b32 s10, s8, 1
	s_or_b32 s9, s9, s10
	s_lshl_b32 s9, s9, 2
	s_lshl_b32 s10, s7, 2
	s_load_dword s29, s[54:55], s9
	s_load_dword s30, s[56:57], s10
	v_add_f32_dpp v132, v132, v132 row_ror:8 row_mask:0xf bank_mask:0x3
	v_add_f32_dpp v133, v133, v133 row_ror:8 row_mask:0xf bank_mask:0x3
	v_add_f32_dpp v134, v134, v134 row_ror:8 row_mask:0xf bank_mask:0x3
	v_add_f32_dpp v135, v135, v135 row_ror:8 row_mask:0xf bank_mask:0x3
	v_add_f32_dpp v136, v136, v136 row_ror:8 row_mask:0xf bank_mask:0x3
	v_add_f32_dpp v137, v137, v137 row_ror:8 row_mask:0xf bank_mask:0x3
	v_add_f32_dpp v138, v138, v138 row_ror:8 row_mask:0xf bank_mask:0x3
	v_add_f32_dpp v139, v139, v139 row_ror:8 row_mask:0xf bank_mask:0x3
	v_add_f32_dpp v132, v140, v140 row_ror:8 row_mask:0xf bank_mask:0xc
	v_add_f32_dpp v133, v141, v141 row_ror:8 row_mask:0xf bank_mask:0xc
	v_add_f32_dpp v134, v142, v142 row_ror:8 row_mask:0xf bank_mask:0xc
	v_add_f32_dpp v135, v143, v143 row_ror:8 row_mask:0xf bank_mask:0xc
	v_add_f32_dpp v136, v144, v144 row_ror:8 row_mask:0xf bank_mask:0xc
	v_add_f32_dpp v137, v145, v145 row_ror:8 row_mask:0xf bank_mask:0xc
	v_add_f32_dpp v138, v146, v146 row_ror:8 row_mask:0xf bank_mask:0xc
	v_add_f32_dpp v139, v147, v147 row_ror:8 row_mask:0xf bank_mask:0xc
	v_add_f32_dpp v132, v132, v132 row_ror:12 row_mask:0xf bank_mask:0x5
	v_add_f32_dpp v133, v133, v133 row_ror:12 row_mask:0xf bank_mask:0x5
	v_add_f32_dpp v134, v134, v134 row_ror:12 row_mask:0xf bank_mask:0x5
	v_add_f32_dpp v135, v135, v135 row_ror:12 row_mask:0xf bank_mask:0x5
	v_add_f32_dpp v132, v136, v136 row_ror:4 row_mask:0xf bank_mask:0xa
	v_add_f32_dpp v133, v137, v137 row_ror:4 row_mask:0xf bank_mask:0xa
	v_add_f32_dpp v134, v138, v138 row_ror:4 row_mask:0xf bank_mask:0xa
	v_add_f32_dpp v135, v139, v139 row_ror:4 row_mask:0xf bank_mask:0xa
	v_add_f32_dpp v140, v132, v132 quad_perm:[2,3,0,1] row_mask:0xf bank_mask:0xf
	v_add_f32_dpp v142, v134, v134 quad_perm:[2,3,0,1] row_mask:0xf bank_mask:0xf
	v_add_f32_dpp v141, v133, v133 quad_perm:[2,3,0,1] row_mask:0xf bank_mask:0xf
	v_add_f32_dpp v143, v135, v135 quad_perm:[2,3,0,1] row_mask:0xf bank_mask:0xf
	v_cndmask_b32_e64 v132, v140, v142, s[76:77]
	v_cndmask_b32_e64 v133, v141, v143, s[76:77]
	s_nop 0
	v_add_f32_dpp v196, v132, v132 quad_perm:[1,0,3,2] row_mask:0xf bank_mask:0xf
	v_add_f32_dpp v197, v133, v133 quad_perm:[1,0,3,2] row_mask:0xf bank_mask:0xf
	v_cndmask_b32_e64 v177, v196, v197, s[78:79]
	s_nop 1
	v_permlane16_swap_b32_e32 v176, v177
	v_add_f32_e32 v178, v176, v177
	v_mul_f32_e32 v178, 0x3e0293ee, v178
	v_add_f32_e32 v178, v178, v192
	v_exp_f32_e64 v198, -v178
	s_nop 0
	v_add_f32_e32 v198, 1.0, v198
	v_rcp_f32_e32 v179, v198
	s_nop 0
	v_sub_f32_e32 v180, 1.0, v179
	v_mov_b32_e32 v181, v180
	s_nop 1
	v_permlane32_swap_b32_e32 v180, v181
	v_mul_f32_e32 v183, v180, v181
	s_nop 1
	v_mul_f32_dpp v183, v183, v183 row_shl:1 row_mask:0xf bank_mask:0xf
	s_nop 1
	v_mul_f32_dpp v183, v183, v183 row_shl:2 row_mask:0xf bank_mask:0xf
	s_nop 1
	v_mul_f32_dpp v183, v183, v183 row_shl:4 row_mask:0xf bank_mask:0xf
	s_nop 1
	v_mul_f32_dpp v183, v183, v183 row_shl:8 row_mask:0xf bank_mask:0xf
	s_nop 0
	v_readlane_b32 s33, v183, 16
	v_mov_b32_e32 v184, 1.0
	s_nop 0
	v_mov_b32_e32 v185, s33
	s_nop 1
	v_mul_f32_dpp v183, v183, v185 quad_perm:[0,1,2,3] row_mask:0x5 bank_mask:0xf
	v_mov_b32_dpp v184, v185 quad_perm:[0,1,2,3] row_mask:0x5 bank_mask:0xf
	s_nop 1
	v_mov_b32_dpp v184, v183 row_shl:1 row_mask:0xf bank_mask:0xf
	v_mul_f32_e32 v186, v179, v184
	s_nop 1
	v_mul_f32_dpp v186, v186, v181 quad_perm:[0,1,2,3] row_mask:0x3 bank_mask:0xf
	s_cmp_eq_u32 s31, 0
	s_cbranch_scc1 .Ldqc_tail
	s_waitcnt lgkmcnt(0)
	s_mov_b32 s12, s29
	s_mov_b32 s13, 0
	s_lshl_b64 s[12:13], s[12:13], 19
	s_and_b32 s14, s8, 1
	s_lshl_b32 s14, s14, 18
	s_lshl_b32 s15, s7, 9
	s_or_b32 s14, s14, s15
	s_or_b32 s80, s12, s14
	s_mov_b32 s81, s13
	s_add_u32 s64, s50, s80
	s_addc_u32 s65, s51, s81
	s_mul_i32 s16, s6, 0x7040
	s_add_u32 s16, s16, s15
	s_add_u32 s16, s60, s16
	s_addc_u32 s17, s61, 0
	global_load_dwordx4 v[156:159], v193, s[16:17]
	s_barrier
; __device__ __forceinline__ void sb_decode_stream(Frame& F, unsigned* qctr, int base, int limit) {
;     ...
;         f32x4 o4 = {0.f, 0.f, 0.f, 0.f};
; #pragma unroll
;         for (int i = 0; i < 16; ++i) { const float aj = __shfl(a, 2 * i + half); o4 += aj * A[i]; }
;         const f32x4 q4n = *(const f32x4*)(SSP(S_PROJ) + (size_t)bn * IN_COLS + hn * HD + 4 * l32);
; #pragma unroll
;         for (int i = 0; i < 16; ++i) A[i] = __builtin_nontemporal_load((const f32x4*)(CK + cbn + (size_t)(2 * i) * stepn));
; #pragma unroll
;         for (int i = 0; i < 16; ++i) { const float aj = __shfl(a, 32 + 2 * i + half); o4 += aj * B[i]; }
; #pragma unroll
;         for (int i = 0; i < 16; ++i) B[i] = __builtin_nontemporal_load((const f32x4*)(CK + cbn + (size_t)(32 + 2 * i) * stepn));
	v_mov_b32_e32 v160, 0
	v_mov_b32_e32 v161, 0
	v_mov_b32_e32 v162, 0
	v_mov_b32_e32 v163, 0
	v_mov_b32_e32 v164, 0
	v_mov_b32_e32 v165, 0
	v_mov_b32_e32 v166, 0
	v_mov_b32_e32 v167, 0
	ds_bpermute_b32 v168, v188, v186 offset:0
	ds_bpermute_b32 v170, v188, v186 offset:4
	ds_bpermute_b32 v172, v188, v186 offset:8
	ds_bpermute_b32 v174, v188, v186 offset:12
	s_waitcnt vmcnt(32) lgkmcnt(3)
	v_pk_fma_f32 v[160:161], v[4:5], v[168:169], v[160:161] op_sel_hi:[1,0,1]
	v_pk_fma_f32 v[162:163], v[6:7], v[168:169], v[162:163] op_sel_hi:[1,0,1]
	global_load_dwordx4 v[4:7], v187, s[64:65] nt
	s_add_u32 s64, s64, 0x2000
	s_addc_u32 s65, s65, 0
	ds_bpermute_b32 v168, v188, v186 offset:16
	s_waitcnt vmcnt(32) lgkmcnt(3)
	v_pk_fma_f32 v[164:165], v[8:9], v[170:171], v[164:165] op_sel_hi:[1,0,1]
	v_pk_fma_f32 v[166:167], v[10:11], v[170:171], v[166:167] op_sel_hi:[1,0,1]
	global_load_dwordx4 v[8:11], v187, s[64:65] nt
	s_add_u32 s64, s64, 0x2000
	s_addc_u32 s65, s65, 0
	ds_bpermute_b32 v170, v188, v186 offset:20
	s_waitcnt vmcnt(32) lgkmcnt(3)
	v_pk_fma_f32 v[160:161], v[12:13], v[172:173], v[160:161] op_sel_hi:[1,0,1]
	v_pk_fma_f32 v[162:163], v[14:15], v[172:173], v[162:163] op_sel_hi:[1,0,1]
	global_load_dwordx4 v[12:15], v187, s[64:65] nt
	s_add_u32 s64, s64, 0x2000
	s_addc_u32 s65, s65, 0
	ds_bpermute_b32 v172, v188, v186 offset:24
	s_waitcnt vmcnt(32) lgkmcnt(3)
	v_pk_fma_f32 v[164:165], v[16:17], v[174:175], v[164:165] op_sel_hi:[1,0,1]
	v_pk_fma_f32 v[166:167], v[18:19], v[174:175], v[166:167] op_sel_hi:[1,0,1]
	global_load_dwordx4 v[16:19], v187, s[64:65] nt
	s_add_u32 s64, s64, 0x2000
	s_addc_u32 s65, s65, 0
	ds_bpermute_b32 v174, v188, v186 offset:28
	s_waitcnt vmcnt(32) lgkmcnt(3)
	v_pk_fma_f32 v[160:161], v[20:21], v[168:169], v[160:161] op_sel_hi:[1,0,1]
	v_pk_fma_f32 v[162:163], v[22:23], v[168:169], v[162:163] op_sel_hi:[1,0,1]
	global_load_dwordx4 v[20:23], v187, s[64:65] nt
	s_add_u32 s64, s64, 0x2000
	s_addc_u32 s65, s65, 0
	ds_bpermute_b32 v168, v188, v186 offset:32
	s_waitcnt vmcnt(32) lgkmcnt(3)
	v_pk_fma_f32 v[164:165], v[24:25], v[170:171], v[164:165] op_sel_hi:[1,0,1]
	v_pk_fma_f32 v[166:167], v[26:27], v[170:171], v[166:167] op_sel_hi:[1,0,1]
	global_load_dwordx4 v[24:27], v187, s[64:65] nt
	s_add_u32 s64, s64, 0x2000
	s_addc_u32 s65, s65, 0
	ds_bpermute_b32 v170, v188, v186 offset:36
	s_waitcnt vmcnt(32) lgkmcnt(3)
	v_pk_fma_f32 v[160:161], v[28:29], v[172:173], v[160:161] op_sel_hi:[1,0,1]
	v_pk_fma_f32 v[162:163], v[30:31], v[172:173], v[162:163] op_sel_hi:[1,0,1]
	global_load_dwordx4 v[28:31], v187, s[64:65] nt
	s_add_u32 s64, s64, 0x2000
	s_addc_u32 s65, s65, 0
	ds_bpermute_b32 v172, v188, v186 offset:40
	s_waitcnt vmcnt(32) lgkmcnt(3)
	v_pk_fma_f32 v[164:165], v[32:33], v[174:175], v[164:165] op_sel_hi:[1,0,1]
	v_pk_fma_f32 v[166:167], v[34:35], v[174:175], v[166:167] op_sel_hi:[1,0,1]
	global_load_dwordx4 v[32:35], v187, s[64:65] nt
	s_add_u32 s64, s64, 0x2000
	s_addc_u32 s65, s65, 0
	ds_bpermute_b32 v174, v188, v186 offset:44
	s_waitcnt vmcnt(32) lgkmcnt(3)
	v_pk_fma_f32 v[160:161], v[36:37], v[168:169], v[160:161] op_sel_hi:[1,0,1]
	v_pk_fma_f32 v[162:163], v[38:39], v[168:169], v[162:163] op_sel_hi:[1,0,1]
	global_load_dwordx4 v[36:39], v187, s[64:65] nt
	s_add_u32 s64, s64, 0x2000
	s_addc_u32 s65, s65, 0
	ds_bpermute_b32 v168, v188, v186 offset:48
	s_waitcnt vmcnt(32) lgkmcnt(3)
	v_pk_fma_f32 v[164:165], v[40:41], v[170:171], v[164:165] op_sel_hi:[1,0,1]
	v_pk_fma_f32 v[166:167], v[42:43], v[170:171], v[166:167] op_sel_hi:[1,0,1]
	global_load_dwordx4 v[40:43], v187, s[64:65] nt
	s_add_u32 s64, s64, 0x2000
	s_addc_u32 s65, s65, 0
	ds_bpermute_b32 v170, v188, v186 offset:52
	s_waitcnt vmcnt(32) lgkmcnt(3)
	v_pk_fma_f32 v[160:161], v[44:45], v[172:173], v[160:161] op_sel_hi:[1,0,1]
	v_pk_fma_f32 v[162:163], v[46:47], v[172:173], v[162:163] op_sel_hi:[1,0,1]
	global_load_dwordx4 v[44:47], v187, s[64:65] nt
	s_add_u32 s64, s64, 0x2000
	s_addc_u32 s65, s65, 0
	ds_bpermute_b32 v172, v188, v186 offset:56
	s_waitcnt vmcnt(32) lgkmcnt(3)
	v_pk_fma_f32 v[164:165], v[48:49], v[174:175], v[164:165] op_sel_hi:[1,0,1]
	v_pk_fma_f32 v[166:167], v[50:51], v[174:175], v[166:167] op_sel_hi:[1,0,1]
	global_load_dwordx4 v[48:51], v187, s[64:65] nt
	s_add_u32 s64, s64, 0x2000
	s_addc_u32 s65, s65, 0
	ds_bpermute_b32 v174, v188, v186 offset:60
	s_waitcnt vmcnt(32) lgkmcnt(3)
	v_pk_fma_f32 v[160:161], v[52:53], v[168:169], v[160:161] op_sel_hi:[1,0,1]
	v_pk_fma_f32 v[162:163], v[54:55], v[168:169], v[162:163] op_sel_hi:[1,0,1]
	global_load_dwordx4 v[52:55], v187, s[64:65] nt
	s_add_u32 s64, s64, 0x2000
	s_addc_u32 s65, s65, 0
	ds_bpermute_b32 v168, v188, v186 offset:64
	s_waitcnt vmcnt(32) lgkmcnt(3)
	v_pk_fma_f32 v[164:165], v[56:57], v[170:171], v[164:165] op_sel_hi:[1,0,1]
	v_pk_fma_f32 v[166:167], v[58:59], v[170:171], v[166:167] op_sel_hi:[1,0,1]
	global_load_dwordx4 v[56:59], v187, s[64:65] nt
	s_add_u32 s64, s64, 0x2000
	s_addc_u32 s65, s65, 0
	ds_bpermute_b32 v170, v188, v186 offset:68
	s_waitcnt vmcnt(32) lgkmcnt(3)
	v_pk_fma_f32 v[160:161], v[60:61], v[172:173], v[160:161] op_sel_hi:[1,0,1]
	v_pk_fma_f32 v[162:163], v[62:63], v[172:173], v[162:163] op_sel_hi:[1,0,1]
	global_load_dwordx4 v[60:63], v187, s[64:65] nt
	s_add_u32 s64, s64, 0x2000
	s_addc_u32 s65, s65, 0
	ds_bpermute_b32 v172, v188, v186 offset:72
	s_waitcnt vmcnt(32) lgkmcnt(3)
	v_pk_fma_f32 v[164:165], v[64:65], v[174:175], v[164:165] op_sel_hi:[1,0,1]
	v_pk_fma_f32 v[166:167], v[66:67], v[174:175], v[166:167] op_sel_hi:[1,0,1]
	global_load_dwordx4 v[64:67], v187, s[64:65] nt
	s_add_u32 s64, s64, 0x2000
	s_addc_u32 s65, s65, 0
	s_barrier
; __device__ __forceinline__ void sb_decode_stream(Frame& F, unsigned* qctr, int base, int limit) {
;     ...
;         f32x4 o4 = {0.f, 0.f, 0.f, 0.f};
; #pragma unroll
;         for (int i = 0; i < 16; ++i) { const float aj = __shfl(a, 2 * i + half); o4 += aj * A[i]; }
;         const f32x4 q4n = *(const f32x4*)(SSP(S_PROJ) + (size_t)bn * IN_COLS + hn * HD + 4 * l32);
; #pragma unroll
;         for (int i = 0; i < 16; ++i) A[i] = __builtin_nontemporal_load((const f32x4*)(CK + cbn + (size_t)(2 * i) * stepn));
; #pragma unroll
;         for (int i = 0; i < 16; ++i) { const float aj = __shfl(a, 32 + 2 * i + half); o4 += aj * B[i]; }
; #pragma unroll
;         for (int i = 0; i < 16; ++i) B[i] = __builtin_nontemporal_load((const f32x4*)(CK + cbn + (size_t)(32 + 2 * i) * stepn));
;         o4.x += __shfl_xor(o4.x, 32); o4.y += __shfl_xor(o4.y, 32); o4.z += __shfl_xor(o4.z, 32); o4.w += __shfl_xor(o4.w, 32);
;         float* P = SSP(S_PART) + ((size_t)bh * DSEG + blk) * DPART;
;         if (half == 0) *(f32x4*)(P + 4 * l32) = o4; if (lane == 0) P[128] = tot;
;         if (!more) break;
;         it = itn; cb = cbn; q4 = q4n;
	ds_bpermute_b32 v174, v188, v186 offset:76
	s_waitcnt vmcnt(32) lgkmcnt(3)
	v_pk_fma_f32 v[160:161], v[68:69], v[168:169], v[160:161] op_sel_hi:[1,0,1]
	v_pk_fma_f32 v[162:163], v[70:71], v[168:169], v[162:163] op_sel_hi:[1,0,1]
	global_load_dwordx4 v[68:71], v187, s[64:65] nt
	s_add_u32 s64, s64, 0x2000
	s_addc_u32 s65, s65, 0
	ds_bpermute_b32 v168, v188, v186 offset:80
	s_waitcnt vmcnt(32) lgkmcnt(3)
	v_pk_fma_f32 v[164:165], v[72:73], v[170:171], v[164:165] op_sel_hi:[1,0,1]
	v_pk_fma_f32 v[166:167], v[74:75], v[170:171], v[166:167] op_sel_hi:[1,0,1]
	global_load_dwordx4 v[72:75], v187, s[64:65] nt
	s_add_u32 s64, s64, 0x2000
	s_addc_u32 s65, s65, 0
	ds_bpermute_b32 v170, v188, v186 offset:84
	s_waitcnt vmcnt(32) lgkmcnt(3)
	v_pk_fma_f32 v[160:161], v[76:77], v[172:173], v[160:161] op_sel_hi:[1,0,1]
	v_pk_fma_f32 v[162:163], v[78:79], v[172:173], v[162:163] op_sel_hi:[1,0,1]
	global_load_dwordx4 v[76:79], v187, s[64:65] nt
	s_add_u32 s64, s64, 0x2000
	s_addc_u32 s65, s65, 0
	ds_bpermute_b32 v172, v188, v186 offset:88
	s_waitcnt vmcnt(32) lgkmcnt(3)
	v_pk_fma_f32 v[164:165], v[80:81], v[174:175], v[164:165] op_sel_hi:[1,0,1]
	v_pk_fma_f32 v[166:167], v[82:83], v[174:175], v[166:167] op_sel_hi:[1,0,1]
	global_load_dwordx4 v[80:83], v187, s[64:65] nt
	s_add_u32 s64, s64, 0x2000
	s_addc_u32 s65, s65, 0
	ds_bpermute_b32 v174, v188, v186 offset:92
	s_waitcnt vmcnt(32) lgkmcnt(3)
	v_pk_fma_f32 v[160:161], v[84:85], v[168:169], v[160:161] op_sel_hi:[1,0,1]
	v_pk_fma_f32 v[162:163], v[86:87], v[168:169], v[162:163] op_sel_hi:[1,0,1]
	global_load_dwordx4 v[84:87], v187, s[64:65] nt
	s_add_u32 s64, s64, 0x2000
	s_addc_u32 s65, s65, 0
	ds_bpermute_b32 v168, v188, v186 offset:96
	s_waitcnt vmcnt(32) lgkmcnt(3)
	v_pk_fma_f32 v[164:165], v[88:89], v[170:171], v[164:165] op_sel_hi:[1,0,1]
	v_pk_fma_f32 v[166:167], v[90:91], v[170:171], v[166:167] op_sel_hi:[1,0,1]
	global_load_dwordx4 v[88:91], v187, s[64:65] nt
	s_add_u32 s64, s64, 0x2000
	s_addc_u32 s65, s65, 0
	ds_bpermute_b32 v170, v188, v186 offset:100
	s_waitcnt vmcnt(32) lgkmcnt(3)
	v_pk_fma_f32 v[160:161], v[92:93], v[172:173], v[160:161] op_sel_hi:[1,0,1]
	v_pk_fma_f32 v[162:163], v[94:95], v[172:173], v[162:163] op_sel_hi:[1,0,1]
	global_load_dwordx4 v[92:95], v187, s[64:65] nt
	s_add_u32 s64, s64, 0x2000
	s_addc_u32 s65, s65, 0
	ds_bpermute_b32 v172, v188, v186 offset:104
	s_waitcnt vmcnt(32) lgkmcnt(3)
	v_pk_fma_f32 v[164:165], v[96:97], v[174:175], v[164:165] op_sel_hi:[1,0,1]
	v_pk_fma_f32 v[166:167], v[98:99], v[174:175], v[166:167] op_sel_hi:[1,0,1]
	global_load_dwordx4 v[96:99], v187, s[64:65] nt
	s_add_u32 s64, s64, 0x2000
	s_addc_u32 s65, s65, 0
	ds_bpermute_b32 v174, v188, v186 offset:108
	s_waitcnt vmcnt(32) lgkmcnt(3)
	v_pk_fma_f32 v[160:161], v[100:101], v[168:169], v[160:161] op_sel_hi:[1,0,1]
	v_pk_fma_f32 v[162:163], v[102:103], v[168:169], v[162:163] op_sel_hi:[1,0,1]
	global_load_dwordx4 v[100:103], v187, s[64:65] nt
	s_add_u32 s64, s64, 0x2000
	s_addc_u32 s65, s65, 0
	ds_bpermute_b32 v168, v188, v186 offset:112
	s_waitcnt vmcnt(32) lgkmcnt(3)
	v_pk_fma_f32 v[164:165], v[104:105], v[170:171], v[164:165] op_sel_hi:[1,0,1]
	v_pk_fma_f32 v[166:167], v[106:107], v[170:171], v[166:167] op_sel_hi:[1,0,1]
	global_load_dwordx4 v[104:107], v187, s[64:65] nt
	s_add_u32 s64, s64, 0x2000
	s_addc_u32 s65, s65, 0
	ds_bpermute_b32 v170, v188, v186 offset:116
	s_waitcnt vmcnt(32) lgkmcnt(3)
	v_pk_fma_f32 v[160:161], v[108:109], v[172:173], v[160:161] op_sel_hi:[1,0,1]
	v_pk_fma_f32 v[162:163], v[110:111], v[172:173], v[162:163] op_sel_hi:[1,0,1]
	global_load_dwordx4 v[108:111], v187, s[64:65] nt
	s_add_u32 s64, s64, 0x2000
	s_addc_u32 s65, s65, 0
	ds_bpermute_b32 v172, v188, v186 offset:120
	s_waitcnt vmcnt(32) lgkmcnt(3)
	v_pk_fma_f32 v[164:165], v[112:113], v[174:175], v[164:165] op_sel_hi:[1,0,1]
	v_pk_fma_f32 v[166:167], v[114:115], v[174:175], v[166:167] op_sel_hi:[1,0,1]
	global_load_dwordx4 v[112:115], v187, s[64:65] nt
	s_add_u32 s64, s64, 0x2000
	s_addc_u32 s65, s65, 0
	ds_bpermute_b32 v174, v188, v186 offset:124
	s_waitcnt vmcnt(32) lgkmcnt(3)
	v_pk_fma_f32 v[160:161], v[116:117], v[168:169], v[160:161] op_sel_hi:[1,0,1]
	v_pk_fma_f32 v[162:163], v[118:119], v[168:169], v[162:163] op_sel_hi:[1,0,1]
	global_load_dwordx4 v[116:119], v187, s[64:65] nt
	s_add_u32 s64, s64, 0x2000
	s_addc_u32 s65, s65, 0
	s_waitcnt vmcnt(32) lgkmcnt(2)
	v_pk_fma_f32 v[164:165], v[120:121], v[170:171], v[164:165] op_sel_hi:[1,0,1]
	v_pk_fma_f32 v[166:167], v[122:123], v[170:171], v[166:167] op_sel_hi:[1,0,1]
	global_load_dwordx4 v[120:123], v187, s[64:65] nt
	s_add_u32 s64, s64, 0x2000
	s_addc_u32 s65, s65, 0
	s_waitcnt vmcnt(32) lgkmcnt(1)
	v_pk_fma_f32 v[160:161], v[124:125], v[172:173], v[160:161] op_sel_hi:[1,0,1]
	v_pk_fma_f32 v[162:163], v[126:127], v[172:173], v[162:163] op_sel_hi:[1,0,1]
	global_load_dwordx4 v[124:127], v187, s[64:65] nt
	s_add_u32 s64, s64, 0x2000
	s_addc_u32 s65, s65, 0
	s_waitcnt vmcnt(32) lgkmcnt(0)
	v_pk_fma_f32 v[164:165], v[128:129], v[174:175], v[164:165] op_sel_hi:[1,0,1]
	v_pk_fma_f32 v[166:167], v[130:131], v[174:175], v[166:167] op_sel_hi:[1,0,1]
	global_load_dwordx4 v[128:131], v187, s[64:65] nt
	s_add_u32 s64, s64, 0x2000
	s_addc_u32 s65, s65, 0
	s_nop 1
	v_pk_add_f32 v[160:161], v[160:161], v[164:165]
	v_pk_add_f32 v[162:163], v[162:163], v[166:167]
	s_nop 1
	v_mov_b32_e32 v164, v160
	v_mov_b32_e32 v165, v161
	v_mov_b32_e32 v166, v162
	v_mov_b32_e32 v167, v163
	v_permlane32_swap_b32_e32 v160, v164
	v_permlane32_swap_b32_e32 v161, v165
	v_permlane32_swap_b32_e32 v162, v166
	v_permlane32_swap_b32_e32 v163, v167
	v_pk_add_f32 v[160:161], v[160:161], v[164:165]
	v_pk_add_f32 v[162:163], v[162:163], v[166:167]
	s_nop 1
	s_mov_b32 exec_hi, 0
	global_store_dwordx4 v193, v[160:163], s[70:71]
	s_mov_b32 exec_lo, 1
	global_store_dword v189, v183, s[70:71] offset:512
	s_mov_b64 exec, -1
	s_mov_b32 s72, s73
	s_branch .Ldqc_loop
